# p4 + M1 epilogue: ds_bpermute lane transpose so four consecutive lanes store 64 contiguous bytes (X chunk permuted early, stores issued after the Y chunk)
# speedup vs baseline: 1.0060x; 1.0015x over previous
.LBB0_1158:
	v_lshl_add_u64 v[152:153], v[138:139], 0, s[62:63]
	s_add_i32 m0, s18, 0x18000
	s_waitcnt vmcnt(2)
	s_barrier
	global_load_lds_dwordx4 v[152:153], off
	v_lshl_add_u64 v[152:153], v[138:139], 0, s[64:65]
	s_add_i32 m0, s18, 0x1a000
	s_add_i32 s22, s18, 0x8000
	global_load_lds_dwordx4 v[152:153], off
	v_lshl_add_u64 v[152:153], v[142:143], 0, s[62:63]
	s_mov_b32 m0, s22
	s_add_i32 s23, s18, 0xa000
	global_load_lds_dwordx4 v[152:153], off
	v_lshl_add_u64 v[142:143], v[142:143], 0, s[64:65]
	s_mov_b32 m0, s23
	s_sext_i32_i16 s11, s2
	global_load_lds_dwordx4 v[142:143], off
	v_lshl_add_u64 v[142:143], v[138:139], 0, s[66:67]
	s_add_i32 m0, s18, 0x1c000
	v_lshl_add_u64 v[138:139], v[138:139], 0, s[68:69]
	global_load_lds_dwordx4 v[142:143], off
	s_add_i32 m0, s18, 0x1e000
	v_and_b32_e32 v142, 15, v0
	global_load_lds_dwordx4 v[138:139], off
	v_lshl_or_b32 v161, s5, 6, v142
	v_lshlrev_b32_e32 v153, 6, v161
	v_and_b32_e32 v154, 48, v0
	s_movk_i32 s2, 0x3c0
	v_lshlrev_b32_e32 v155, 2, v0
	v_and_or_b32 v143, v153, s2, v154
	s_lshl_b32 s2, s5, 13
	v_and_b32_e32 v155, 32, v155
	v_bitop3_b32 v156, v143, s2, v155 bitop3:0xde
	s_lshl_b32 s2, s4, 5
	s_mov_b64 s[6:7], 0x12200000
	s_and_b32 s5, s2, 0x60
	v_lshl_add_u64 v[138:139], v[140:141], 0, s[6:7]
	v_lshl_or_b32 v142, v142, 6, v154
	s_lshl_b32 s6, s5, 7
	v_bitop3_b32 v163, v142, s6, v155 bitop3:0xde
	v_and_b32_e32 v142, 48, v145
	v_mov_b32_e32 v143, v1
	v_and_b32_e32 v208, 63, v0
	v_lshrrev_b32_e32 v209, 2, v208
	v_and_b32_e32 v238, 3, v208
	v_lshl_add_u32 v171, v238, 4, v209
	v_lshlrev_b32_e32 v171, 2, v171
	v_and_b32_e32 v239, 15, v208
	v_sub_u32_e32 v255, v209, v239
	v_lshlrev_b32_e32 v238, 3, v238
	v_lshrrev_b32_e32 v152, 1, v0
	s_lshl_b32 s6, s4, 1
	v_bfe_u32 v0, v0, 2, 4
	v_lshl_add_u64 v[140:141], v[140:141], 0, v[142:143]
	v_lshlrev_b32_e32 v142, 15, v146
	v_or_b32_e32 v166, s2, v0
	s_or_b32 s2, s6, 1
	v_and_b32_e32 v142, 0xffff0000, v142
	s_waitcnt vmcnt(0)
	s_lshl_b32 s4, s4, 11
	s_lshl_b32 s6, s2, 10
	v_readlane_b32 s7, v254, 11
	v_lshl_add_u32 v142, v144, 12, v142
	v_and_b32_e32 v143, 1, v146
	v_lshl_or_b32 v167, s2, 4, v0
	s_cmpk_lt_u32 s3, 0x100
	s_mov_b64 s[8:9], 0x3c800000
	v_add_u32_e32 v0, s7, v153
	v_lshl_or_b32 v142, v143, 6, v142
	s_cselect_b64 s[2:3], -1, 0
	s_ashr_i32 s24, s14, 31
	v_lshl_add_u64 v[140:141], v[140:141], 0, s[8:9]
	v_and_or_b32 v168, v152, 24, s5
	v_or_b32_e32 v168, s5, v238
	v_lshl_add_u32 v142, v147, 1, v142
	v_mov_b32_e32 v143, v1
	s_mov_b32 s25, 0
	v_add_u32_e32 v169, 0, v156
	v_add_u32_e32 v170, v0, v154
	s_add_i32 s26, s7, s4
	s_add_i32 s27, s7, s6
	s_barrier
	s_branch .LBB0_1161

.LBB0_1167:
.LBB0_1169:
	ds_read_b128 v[150:153], v170
	ds_read_b128 v[154:157], v170 offset:2048
	v_add_u32_e32 v148, s7, v161
	v_add_u32_e32 v148, v148, v255
	v_lshl_or_b32 v164, s11, 8, v168
	v_ashrrev_i32_e32 v165, 31, v164
	s_waitcnt lgkmcnt(0)
	v_lshlrev_b32_e32 v0, 16, v150
	v_and_b32_e32 v149, 0xffff0000, v150
	v_add_f32_e32 v0, v0, v149
	v_lshlrev_b32_e32 v149, 16, v151
	v_and_b32_e32 v150, 0xffff0000, v151
	v_add_f32_e32 v149, v149, v150
	v_add_f32_e32 v0, v0, v149
	v_lshlrev_b32_e32 v149, 16, v152
	v_and_b32_e32 v150, 0xffff0000, v152
	v_add_f32_e32 v149, v149, v150
	v_lshlrev_b32_e32 v150, 16, v153
	v_and_b32_e32 v151, 0xffff0000, v153
	v_add_f32_e32 v150, v150, v151
	v_add_f32_e32 v149, v149, v150
	v_add_f32_e32 v0, v0, v149
	v_mov_b32_e32 v149, v0
	ds_read_b128 v[150:153], v170 offset:1024
	ds_read_b128 v[172:175], v170 offset:8192
	v_permlane16_swap_b32_e32 v0, v149
	v_add_f32_e32 v0, v0, v149
	v_mov_b32_e32 v149, v0
	s_nop 1
	v_permlane32_swap_b32_e32 v0, v149
	v_add_f32_e32 v0, v0, v149
	s_waitcnt lgkmcnt(0)
	v_lshlrev_b32_e32 v149, 16, v150
	v_and_b32_e32 v150, 0xffff0000, v150
	v_add_f32_e32 v149, v149, v150
	v_lshlrev_b32_e32 v150, 16, v151
	v_and_b32_e32 v151, 0xffff0000, v151
	v_add_f32_e32 v150, v150, v151
	v_add_f32_e32 v149, v149, v150
	v_lshlrev_b32_e32 v150, 16, v152
	v_and_b32_e32 v151, 0xffff0000, v152
	v_add_f32_e32 v150, v150, v151
	v_lshlrev_b32_e32 v151, 16, v153
	v_and_b32_e32 v152, 0xffff0000, v153
	v_add_f32_e32 v151, v151, v152
	v_add_f32_e32 v150, v150, v151
	v_add_f32_e32 v149, v149, v150
	v_mov_b32_e32 v150, v149
	s_nop 1
	v_permlane16_swap_b32_e32 v149, v150
	v_add_f32_e32 v149, v149, v150
	v_mov_b32_e32 v150, v149
	s_nop 1
	v_permlane32_swap_b32_e32 v149, v150
	v_add_f32_e32 v149, v149, v150
	v_fmamk_f32 v149, v149, 0x3a000000, v240
	v_rsq_f32_e32 v152, v149
	v_lshlrev_b32_e32 v149, 16, v154
	v_and_b32_e32 v150, 0xffff0000, v154
	v_add_f32_e32 v149, v149, v150
	v_lshlrev_b32_e32 v150, 16, v155
	v_and_b32_e32 v151, 0xffff0000, v155
	v_add_f32_e32 v150, v150, v151
	v_add_f32_e32 v149, v149, v150
	v_lshlrev_b32_e32 v150, 16, v156
	v_and_b32_e32 v151, 0xffff0000, v156
	v_add_f32_e32 v150, v150, v151
	v_lshlrev_b32_e32 v151, 16, v157
	v_and_b32_e32 v153, 0xffff0000, v157
	v_add_f32_e32 v151, v151, v153
	v_add_f32_e32 v150, v150, v151
	v_add_f32_e32 v149, v149, v150
	v_mov_b32_e32 v150, v149
	s_nop 1
	v_permlane16_swap_b32_e32 v149, v150
	v_add_f32_e32 v149, v149, v150
	ds_read_b128 v[154:157], v170 offset:3072
	v_mov_b32_e32 v150, v149
	s_nop 1
	v_permlane32_swap_b32_e32 v149, v150
	v_add_f32_e32 v149, v149, v150
	v_fmamk_f32 v149, v149, 0x3a000000, v240
	v_rsq_f32_e32 v150, v149
	s_waitcnt lgkmcnt(0)
	v_lshlrev_b32_e32 v149, 16, v154
	v_and_b32_e32 v151, 0xffff0000, v154
	v_add_f32_e32 v149, v149, v151
	v_lshlrev_b32_e32 v151, 16, v155
	v_and_b32_e32 v153, 0xffff0000, v155
	v_add_f32_e32 v151, v151, v153
	v_add_f32_e32 v149, v149, v151
	v_lshlrev_b32_e32 v151, 16, v156
	v_and_b32_e32 v153, 0xffff0000, v156
	v_add_f32_e32 v151, v151, v153
	v_lshlrev_b32_e32 v153, 16, v157
	v_and_b32_e32 v154, 0xffff0000, v157
	v_add_f32_e32 v153, v153, v154
	v_add_f32_e32 v151, v151, v153
	v_add_f32_e32 v149, v149, v151
	v_mov_b32_e32 v151, v149
	s_nop 1
	v_permlane16_swap_b32_e32 v149, v151
	v_add_f32_e32 v149, v149, v151
	v_mov_b32_e32 v151, v149
	s_nop 1
	v_permlane32_swap_b32_e32 v149, v151
	v_add_f32_e32 v149, v149, v151
	v_fmamk_f32 v149, v149, 0x3a000000, v240
	v_rsq_f32_e32 v156, v149
	v_lshlrev_b32_e32 v149, 16, v172
	v_and_b32_e32 v151, 0xffff0000, v172
	s_mov_b64 vcc, s[2:3]
	s_cbranch_vccz .Lalign_skip_2
	s_barrier
.Lalign_skip_2:
	v_add_f32_e32 v149, v149, v151
	v_lshlrev_b32_e32 v151, 16, v173
	v_and_b32_e32 v153, 0xffff0000, v173
	v_add_f32_e32 v151, v151, v153
	v_add_f32_e32 v149, v149, v151
	v_lshlrev_b32_e32 v151, 16, v174
	v_and_b32_e32 v153, 0xffff0000, v174
	v_add_f32_e32 v151, v151, v153
	v_lshlrev_b32_e32 v153, 16, v175
	v_and_b32_e32 v154, 0xffff0000, v175
	v_add_f32_e32 v153, v153, v154
	v_add_f32_e32 v151, v151, v153
	v_add_f32_e32 v149, v149, v151
	v_mov_b32_e32 v151, v149
	s_nop 1
	v_permlane16_swap_b32_e32 v149, v151
	v_add_f32_e32 v149, v149, v151
	ds_read_b128 v[172:175], v170 offset:9216
	v_mov_b32_e32 v151, v149
	s_nop 1
	v_permlane32_swap_b32_e32 v149, v151
	v_add_f32_e32 v149, v149, v151
	v_fmamk_f32 v149, v149, 0x3a000000, v240
	v_rsq_f32_e32 v154, v149
	s_waitcnt lgkmcnt(0)
	v_lshlrev_b32_e32 v149, 16, v172
	v_and_b32_e32 v151, 0xffff0000, v172
	v_add_f32_e32 v149, v149, v151
	v_lshlrev_b32_e32 v151, 16, v173
	v_and_b32_e32 v153, 0xffff0000, v173
	v_add_f32_e32 v151, v151, v153
	v_add_f32_e32 v149, v149, v151
	v_lshlrev_b32_e32 v151, 16, v174
	v_and_b32_e32 v153, 0xffff0000, v174
	v_add_f32_e32 v151, v151, v153
	v_lshlrev_b32_e32 v153, 16, v175
	v_and_b32_e32 v155, 0xffff0000, v175
	v_add_f32_e32 v153, v153, v155
	v_add_f32_e32 v151, v151, v153
	v_add_f32_e32 v149, v149, v151
	v_mov_b32_e32 v151, v149
	s_nop 1
	v_permlane16_swap_b32_e32 v149, v151
	v_add_f32_e32 v149, v149, v151
	ds_read_b128 v[172:175], v170 offset:10240
	v_mov_b32_e32 v151, v149
	s_nop 1
	v_permlane32_swap_b32_e32 v149, v151
	v_add_f32_e32 v149, v149, v151
	v_fmamk_f32 v149, v149, 0x3a000000, v240
	v_rsq_f32_e32 v160, v149
	s_waitcnt lgkmcnt(0)
	v_lshlrev_b32_e32 v149, 16, v172
	v_and_b32_e32 v151, 0xffff0000, v172
	v_add_f32_e32 v149, v149, v151
	v_lshlrev_b32_e32 v151, 16, v173
	v_and_b32_e32 v153, 0xffff0000, v173
	v_add_f32_e32 v151, v151, v153
	v_add_f32_e32 v149, v149, v151
	v_lshlrev_b32_e32 v151, 16, v174
	v_and_b32_e32 v153, 0xffff0000, v174
	v_add_f32_e32 v151, v151, v153
	v_lshlrev_b32_e32 v153, 16, v175
	v_and_b32_e32 v155, 0xffff0000, v175
	v_add_f32_e32 v153, v153, v155
	v_add_f32_e32 v151, v151, v153
	v_add_f32_e32 v149, v149, v151
	v_mov_b32_e32 v151, v149
	s_nop 1
	v_permlane16_swap_b32_e32 v149, v151
	v_add_f32_e32 v149, v149, v151
	ds_read_b128 v[172:175], v170 offset:11264
	v_mov_b32_e32 v151, v149
	s_nop 1
	v_permlane32_swap_b32_e32 v149, v151
	v_add_f32_e32 v149, v149, v151
	v_fmamk_f32 v149, v149, 0x3a000000, v240
	v_rsq_f32_e32 v158, v149
	s_waitcnt lgkmcnt(0)
	v_lshlrev_b32_e32 v149, 16, v172
	v_and_b32_e32 v151, 0xffff0000, v172
	v_add_f32_e32 v149, v149, v151
	v_lshlrev_b32_e32 v151, 16, v173
	v_and_b32_e32 v153, 0xffff0000, v173
	v_add_f32_e32 v151, v151, v153
	v_add_f32_e32 v149, v149, v151
	v_lshlrev_b32_e32 v151, 16, v174
	v_and_b32_e32 v153, 0xffff0000, v174
	v_add_f32_e32 v151, v151, v153
	v_lshlrev_b32_e32 v153, 16, v175
	v_and_b32_e32 v155, 0xffff0000, v175
	v_add_f32_e32 v153, v153, v155
	v_add_f32_e32 v151, v151, v153
	v_add_f32_e32 v149, v149, v151
	v_mov_b32_e32 v151, v149
	v_fmamk_f32 v0, v0, 0x3a000000, v240
	s_nop 0
	v_permlane16_swap_b32_e32 v149, v151
	v_rsq_f32_e32 v0, v0
	v_add_f32_e32 v149, v149, v151
	v_mov_b32_e32 v151, v149
	s_nop 1
	v_permlane32_swap_b32_e32 v149, v151
	v_add_f32_e32 v149, v149, v151
	v_fmamk_f32 v149, v149, 0x3a000000, v240
	v_pk_mul_f32 v[122:123], v[122:123], v[0:1] op_sel_hi:[1,0]
	v_rsq_f32_e32 v162, v149
	v_ashrrev_i32_e32 v149, 31, v148
	v_max_f32_e32 v122, 0, v122
	v_lshl_add_u64 v[172:173], v[164:165], 1, v[138:139]
	v_lshlrev_b64 v[164:165], 14, v[148:149]
	v_pk_mul_f32 v[124:125], v[124:125], v[0:1] op_sel_hi:[1,0]
	v_mul_f32_e32 v149, v122, v122
	v_max_f32_e32 v122, 0, v123
	v_pk_mul_f32 v[126:127], v[126:127], v[0:1] op_sel_hi:[1,0]
	v_mul_f32_e32 v151, v122, v122
	v_max_f32_e32 v122, 0, v124
	v_pk_mul_f32 v[114:115], v[114:115], v[0:1] op_sel_hi:[1,0]
	v_pk_mul_f32 v[128:129], v[128:129], v[0:1] op_sel_hi:[1,0]
	v_max_f32_e32 v126, 0, v126
	v_max_f32_e32 v127, 0, v127
	v_mul_f32_e32 v153, v122, v122
	v_max_f32_e32 v122, 0, v125
	v_pk_mul_f32 v[120:121], v[120:121], v[0:1] op_sel_hi:[1,0]
	v_pk_mul_f32 v[118:119], v[118:119], v[0:1] op_sel_hi:[1,0]
	v_max_f32_e32 v114, 0, v114
	v_lshl_add_u64 v[164:165], v[172:173], 0, v[164:165]
	v_mul_f32_e32 v126, v126, v126
	v_mul_f32_e32 v127, v127, v127
	v_max_f32_e32 v128, 0, v128
	v_max_f32_e32 v129, 0, v129
	v_mul_f32_e32 v125, v122, v122
	v_cvt_pk_bf16_f32 v122, v126, v127
	v_pk_mul_f32 v[116:117], v[116:117], v[0:1] op_sel_hi:[1,0]
	v_max_f32_e32 v0, 0, v118
	v_max_f32_e32 v118, 0, v119
	v_max_f32_e32 v119, 0, v120
	v_max_f32_e32 v120, 0, v121
	v_mul_f32_e32 v121, v114, v114
	v_max_f32_e32 v114, 0, v115
	v_mul_f32_e32 v128, v128, v128
	v_mul_f32_e32 v129, v129, v129
	v_cvt_pk_bf16_f32 v123, v128, v129
	v_cvt_pk_bf16_f32 v124, v149, v151
	v_cvt_pk_bf16_f32 v125, v153, v125
	ds_bpermute_b32 v122, v171, v122
	ds_bpermute_b32 v123, v171, v123
	ds_bpermute_b32 v124, v171, v124
	ds_bpermute_b32 v125, v171, v125
	v_pk_mul_f32 v[106:107], v[106:107], v[152:153] op_sel_hi:[1,0]
	v_mul_f32_e32 v0, v0, v0
	v_mul_f32_e32 v238, v114, v114
	v_max_f32_e32 v114, 0, v116
	v_mul_f32_e32 v239, v114, v114
	v_max_f32_e32 v114, 0, v117
	v_mul_f32_e32 v118, v118, v118
	v_mul_f32_e32 v117, v114, v114
	v_cvt_pk_bf16_f32 v114, v0, v118
	v_pk_mul_f32 v[112:113], v[112:113], v[152:153] op_sel_hi:[1,0]
	v_pk_mul_f32 v[110:111], v[110:111], v[152:153] op_sel_hi:[1,0]
	v_max_f32_e32 v106, 0, v106
	v_mul_f32_e32 v119, v119, v119
	v_mul_f32_e32 v120, v120, v120
	v_cvt_pk_bf16_f32 v115, v119, v120
	v_cvt_pk_bf16_f32 v116, v121, v238
	v_cvt_pk_bf16_f32 v117, v239, v117
	ds_bpermute_b32 v114, v171, v114
	ds_bpermute_b32 v115, v171, v115
	ds_bpermute_b32 v116, v171, v116
	ds_bpermute_b32 v117, v171, v117
	s_waitcnt lgkmcnt(4)
	global_store_dwordx4 v[164:165], v[122:125], off
	s_waitcnt lgkmcnt(0)
	global_store_dwordx4 v[164:165], v[114:117], off offset:256
	v_pk_mul_f32 v[108:109], v[108:109], v[152:153] op_sel_hi:[1,0]
	v_max_f32_e32 v0, 0, v110
	v_or_b32_e32 v114, 16, v148
	v_max_f32_e32 v110, 0, v111
	v_max_f32_e32 v111, 0, v112
	v_max_f32_e32 v112, 0, v113
	v_mul_f32_e32 v113, v106, v106
	v_max_f32_e32 v106, 0, v107
	v_ashrrev_i32_e32 v115, 31, v114
	v_mul_f32_e32 v116, v106, v106
	v_max_f32_e32 v106, 0, v108
	v_pk_mul_f32 v[98:99], v[98:99], v[152:153] op_sel_hi:[1,0]
	v_lshlrev_b64 v[114:115], 14, v[114:115]
	v_mul_f32_e32 v0, v0, v0
	v_mul_f32_e32 v117, v106, v106
	v_max_f32_e32 v106, 0, v109
	v_pk_mul_f32 v[104:105], v[104:105], v[152:153] op_sel_hi:[1,0]
	v_pk_mul_f32 v[102:103], v[102:103], v[152:153] op_sel_hi:[1,0]
	v_max_f32_e32 v98, 0, v98
	v_lshl_add_u64 v[114:115], v[172:173], 0, v[114:115]
	v_mul_f32_e32 v110, v110, v110
	v_mul_f32_e32 v109, v106, v106
	v_cvt_pk_bf16_f32 v106, v0, v110
	v_pk_mul_f32 v[100:101], v[100:101], v[152:153] op_sel_hi:[1,0]
	v_max_f32_e32 v0, 0, v102
	v_max_f32_e32 v102, 0, v103
	v_max_f32_e32 v103, 0, v104
	v_max_f32_e32 v104, 0, v105
	v_mul_f32_e32 v105, v98, v98
	v_max_f32_e32 v98, 0, v99
	v_mul_f32_e32 v111, v111, v111
	v_mul_f32_e32 v112, v112, v112
	v_cvt_pk_bf16_f32 v107, v111, v112
	v_cvt_pk_bf16_f32 v108, v113, v116
	v_cvt_pk_bf16_f32 v109, v117, v109
	ds_bpermute_b32 v106, v171, v106
	ds_bpermute_b32 v107, v171, v107
	ds_bpermute_b32 v108, v171, v108
	ds_bpermute_b32 v109, v171, v109
	v_pk_mul_f32 v[90:91], v[90:91], v[150:151] op_sel_hi:[1,0]
	v_mul_f32_e32 v0, v0, v0
	v_mul_f32_e32 v238, v98, v98
	v_max_f32_e32 v98, 0, v100
	v_mul_f32_e32 v239, v98, v98
	v_max_f32_e32 v98, 0, v101
	v_mul_f32_e32 v102, v102, v102
	v_mul_f32_e32 v101, v98, v98
	v_cvt_pk_bf16_f32 v98, v0, v102
	v_pk_mul_f32 v[96:97], v[96:97], v[150:151] op_sel_hi:[1,0]
	v_pk_mul_f32 v[94:95], v[94:95], v[150:151] op_sel_hi:[1,0]
	v_max_f32_e32 v90, 0, v90
	v_mul_f32_e32 v103, v103, v103
	v_mul_f32_e32 v104, v104, v104
	v_cvt_pk_bf16_f32 v99, v103, v104
	v_cvt_pk_bf16_f32 v100, v105, v238
	v_cvt_pk_bf16_f32 v101, v239, v101
	ds_bpermute_b32 v98, v171, v98
	ds_bpermute_b32 v99, v171, v99
	ds_bpermute_b32 v100, v171, v100
	ds_bpermute_b32 v101, v171, v101
	s_waitcnt lgkmcnt(4)
	global_store_dwordx4 v[114:115], v[106:109], off
	s_waitcnt lgkmcnt(0)
	global_store_dwordx4 v[114:115], v[98:101], off offset:256
	v_pk_mul_f32 v[92:93], v[92:93], v[150:151] op_sel_hi:[1,0]
	v_max_f32_e32 v0, 0, v94
	v_or_b32_e32 v98, 32, v148
	v_max_f32_e32 v94, 0, v95
	v_max_f32_e32 v95, 0, v96
	v_max_f32_e32 v96, 0, v97
	v_mul_f32_e32 v97, v90, v90
	v_max_f32_e32 v90, 0, v91
	v_ashrrev_i32_e32 v99, 31, v98
	v_mul_f32_e32 v100, v90, v90
	v_max_f32_e32 v90, 0, v92
	v_pk_mul_f32 v[82:83], v[82:83], v[150:151] op_sel_hi:[1,0]
	v_lshlrev_b64 v[98:99], 14, v[98:99]
	v_mul_f32_e32 v0, v0, v0
	v_mul_f32_e32 v101, v90, v90
	v_max_f32_e32 v90, 0, v93
	v_pk_mul_f32 v[88:89], v[88:89], v[150:151] op_sel_hi:[1,0]
	v_pk_mul_f32 v[86:87], v[86:87], v[150:151] op_sel_hi:[1,0]
	v_max_f32_e32 v82, 0, v82
	v_lshl_add_u64 v[98:99], v[172:173], 0, v[98:99]
	v_mul_f32_e32 v94, v94, v94
	v_mul_f32_e32 v93, v90, v90
	v_cvt_pk_bf16_f32 v90, v0, v94
	v_pk_mul_f32 v[84:85], v[84:85], v[150:151] op_sel_hi:[1,0]
	v_max_f32_e32 v0, 0, v86
	v_max_f32_e32 v86, 0, v87
	v_max_f32_e32 v87, 0, v88
	v_max_f32_e32 v88, 0, v89
	v_mul_f32_e32 v89, v82, v82
	v_max_f32_e32 v82, 0, v83
	v_mul_f32_e32 v95, v95, v95
	v_mul_f32_e32 v96, v96, v96
	v_cvt_pk_bf16_f32 v91, v95, v96
	v_cvt_pk_bf16_f32 v92, v97, v100
	v_cvt_pk_bf16_f32 v93, v101, v93
	ds_bpermute_b32 v90, v171, v90
	ds_bpermute_b32 v91, v171, v91
	ds_bpermute_b32 v92, v171, v92
	ds_bpermute_b32 v93, v171, v93
	v_pk_mul_f32 v[74:75], v[74:75], v[156:157] op_sel_hi:[1,0]
	v_mul_f32_e32 v0, v0, v0
	v_mul_f32_e32 v238, v82, v82
	v_max_f32_e32 v82, 0, v84
	v_mul_f32_e32 v239, v82, v82
	v_max_f32_e32 v82, 0, v85
	v_mul_f32_e32 v86, v86, v86
	v_mul_f32_e32 v85, v82, v82
	v_cvt_pk_bf16_f32 v82, v0, v86
	v_pk_mul_f32 v[80:81], v[80:81], v[156:157] op_sel_hi:[1,0]
	v_pk_mul_f32 v[78:79], v[78:79], v[156:157] op_sel_hi:[1,0]
	v_max_f32_e32 v74, 0, v74
	v_mul_f32_e32 v87, v87, v87
	v_mul_f32_e32 v88, v88, v88
	v_cvt_pk_bf16_f32 v83, v87, v88
	v_cvt_pk_bf16_f32 v84, v89, v238
	v_cvt_pk_bf16_f32 v85, v239, v85
	ds_bpermute_b32 v82, v171, v82
	ds_bpermute_b32 v83, v171, v83
	ds_bpermute_b32 v84, v171, v84
	ds_bpermute_b32 v85, v171, v85
	s_waitcnt lgkmcnt(4)
	global_store_dwordx4 v[98:99], v[90:93], off
	s_waitcnt lgkmcnt(0)
	global_store_dwordx4 v[98:99], v[82:85], off offset:256
	v_pk_mul_f32 v[76:77], v[76:77], v[156:157] op_sel_hi:[1,0]
	v_max_f32_e32 v0, 0, v78
	v_or_b32_e32 v82, 48, v148
	v_max_f32_e32 v78, 0, v79
	v_max_f32_e32 v79, 0, v80
	v_max_f32_e32 v80, 0, v81
	v_mul_f32_e32 v81, v74, v74
	v_max_f32_e32 v74, 0, v75
	v_ashrrev_i32_e32 v83, 31, v82
	v_mul_f32_e32 v84, v74, v74
	v_max_f32_e32 v74, 0, v76
	v_pk_mul_f32 v[66:67], v[66:67], v[156:157] op_sel_hi:[1,0]
	v_lshlrev_b64 v[82:83], 14, v[82:83]
	v_mul_f32_e32 v0, v0, v0
	v_mul_f32_e32 v85, v74, v74
	v_max_f32_e32 v74, 0, v77
	v_pk_mul_f32 v[72:73], v[72:73], v[156:157] op_sel_hi:[1,0]
	v_pk_mul_f32 v[70:71], v[70:71], v[156:157] op_sel_hi:[1,0]
	v_max_f32_e32 v66, 0, v66
	v_lshl_add_u64 v[82:83], v[172:173], 0, v[82:83]
	v_mul_f32_e32 v78, v78, v78
	v_mul_f32_e32 v77, v74, v74
	v_cvt_pk_bf16_f32 v74, v0, v78
	v_pk_mul_f32 v[68:69], v[68:69], v[156:157] op_sel_hi:[1,0]
	v_max_f32_e32 v0, 0, v70
	v_max_f32_e32 v70, 0, v71
	v_max_f32_e32 v71, 0, v72
	v_max_f32_e32 v72, 0, v73
	v_mul_f32_e32 v73, v66, v66
	v_max_f32_e32 v66, 0, v67
	v_mul_f32_e32 v79, v79, v79
	v_mul_f32_e32 v80, v80, v80
	v_cvt_pk_bf16_f32 v75, v79, v80
	v_cvt_pk_bf16_f32 v76, v81, v84
	v_cvt_pk_bf16_f32 v77, v85, v77
	ds_bpermute_b32 v74, v171, v74
	ds_bpermute_b32 v75, v171, v75
	ds_bpermute_b32 v76, v171, v76
	ds_bpermute_b32 v77, v171, v77
	v_pk_mul_f32 v[58:59], v[58:59], v[154:155] op_sel_hi:[1,0]
	v_mul_f32_e32 v0, v0, v0
	v_mul_f32_e32 v238, v66, v66
	v_max_f32_e32 v66, 0, v68
	v_mul_f32_e32 v239, v66, v66
	v_max_f32_e32 v66, 0, v69
	v_pk_mul_f32 v[64:65], v[64:65], v[154:155] op_sel_hi:[1,0]
	v_pk_mul_f32 v[62:63], v[62:63], v[154:155] op_sel_hi:[1,0]
	v_max_f32_e32 v58, 0, v58
	v_mul_f32_e32 v70, v70, v70
	v_mul_f32_e32 v71, v71, v71
	v_mul_f32_e32 v72, v72, v72
	v_mul_f32_e32 v69, v66, v66
	v_cvt_pk_bf16_f32 v66, v0, v70
	v_cvt_pk_bf16_f32 v67, v71, v72
	v_cvt_pk_bf16_f32 v68, v73, v238
	v_pk_mul_f32 v[60:61], v[60:61], v[154:155] op_sel_hi:[1,0]
	v_max_f32_e32 v0, 0, v62
	v_max_f32_e32 v62, 0, v63
	v_max_f32_e32 v63, 0, v64
	v_max_f32_e32 v64, 0, v65
	v_mul_f32_e32 v65, v58, v58
	v_max_f32_e32 v58, 0, v59
	v_cvt_pk_bf16_f32 v69, v239, v69
	ds_bpermute_b32 v66, v171, v66
	ds_bpermute_b32 v67, v171, v67
	ds_bpermute_b32 v68, v171, v68
	ds_bpermute_b32 v69, v171, v69
	s_waitcnt lgkmcnt(4)
	global_store_dwordx4 v[82:83], v[74:77], off
	s_waitcnt lgkmcnt(0)
	global_store_dwordx4 v[82:83], v[66:69], off offset:256
	v_mul_f32_e32 v62, v62, v62
	s_mov_b32 s7, 0x200000
	v_mul_f32_e32 v68, v58, v58
	v_max_f32_e32 v58, 0, v60
	v_mul_f32_e32 v69, v58, v58
	v_max_f32_e32 v58, 0, v61
	v_pk_mul_f32 v[50:51], v[50:51], v[154:155] op_sel_hi:[1,0]
	v_mul_f32_e32 v0, v0, v0
	v_mul_f32_e32 v63, v63, v63
	v_mul_f32_e32 v61, v58, v58
	v_cvt_pk_bf16_f32 v58, v0, v62
	v_add_co_u32_e32 v62, vcc, s7, v164
	v_pk_mul_f32 v[56:57], v[56:57], v[154:155] op_sel_hi:[1,0]
	v_pk_mul_f32 v[54:55], v[54:55], v[154:155] op_sel_hi:[1,0]
	v_max_f32_e32 v50, 0, v50
	v_mul_f32_e32 v64, v64, v64
	v_cvt_pk_bf16_f32 v59, v63, v64
	v_addc_co_u32_e32 v63, vcc, 0, v165, vcc
	v_pk_mul_f32 v[52:53], v[52:53], v[154:155] op_sel_hi:[1,0]
	v_max_f32_e32 v0, 0, v54
	v_max_f32_e32 v54, 0, v55
	v_max_f32_e32 v55, 0, v56
	v_max_f32_e32 v56, 0, v57
	v_mul_f32_e32 v57, v50, v50
	v_max_f32_e32 v50, 0, v51
	v_cvt_pk_bf16_f32 v60, v65, v68
	v_cvt_pk_bf16_f32 v61, v69, v61
	ds_bpermute_b32 v58, v171, v58
	ds_bpermute_b32 v59, v171, v59
	ds_bpermute_b32 v60, v171, v60
	ds_bpermute_b32 v61, v171, v61
	v_pk_mul_f32 v[42:43], v[42:43], v[160:161] op_sel_hi:[1,0]
	v_mul_f32_e32 v0, v0, v0
	v_mul_f32_e32 v238, v50, v50
	v_max_f32_e32 v50, 0, v52
	v_mul_f32_e32 v239, v50, v50
	v_max_f32_e32 v50, 0, v53
	v_pk_mul_f32 v[48:49], v[48:49], v[160:161] op_sel_hi:[1,0]
	v_pk_mul_f32 v[46:47], v[46:47], v[160:161] op_sel_hi:[1,0]
	v_max_f32_e32 v42, 0, v42
	v_lshl_add_u64 v[66:67], v[164:165], 0, s[50:51]
	v_mul_f32_e32 v54, v54, v54
	v_mul_f32_e32 v55, v55, v55
	v_mul_f32_e32 v56, v56, v56
	v_mul_f32_e32 v53, v50, v50
	v_cvt_pk_bf16_f32 v50, v0, v54
	v_cvt_pk_bf16_f32 v51, v55, v56
	v_cvt_pk_bf16_f32 v52, v57, v238
	v_pk_mul_f32 v[44:45], v[44:45], v[160:161] op_sel_hi:[1,0]
	v_max_f32_e32 v0, 0, v46
	v_max_f32_e32 v46, 0, v47
	v_max_f32_e32 v47, 0, v48
	v_max_f32_e32 v48, 0, v49
	v_mul_f32_e32 v49, v42, v42
	v_max_f32_e32 v42, 0, v43
	v_cvt_pk_bf16_f32 v53, v239, v53
	ds_bpermute_b32 v50, v171, v50
	ds_bpermute_b32 v51, v171, v51
	ds_bpermute_b32 v52, v171, v52
	ds_bpermute_b32 v53, v171, v53
	s_waitcnt lgkmcnt(4)
	global_store_dwordx4 v[62:63], v[58:61], off
	s_waitcnt lgkmcnt(0)
	global_store_dwordx4 v[62:63], v[50:53], off offset:256
	v_mul_f32_e32 v46, v46, v46
	s_mov_b32 s7, 0x240000
	v_mul_f32_e32 v52, v42, v42
	v_max_f32_e32 v42, 0, v44
	v_mul_f32_e32 v53, v42, v42
	v_max_f32_e32 v42, 0, v45
	v_pk_mul_f32 v[34:35], v[34:35], v[160:161] op_sel_hi:[1,0]
	v_mul_f32_e32 v0, v0, v0
	v_mul_f32_e32 v47, v47, v47
	v_mul_f32_e32 v45, v42, v42
	v_cvt_pk_bf16_f32 v42, v0, v46
	v_add_co_u32_e32 v46, vcc, s7, v164
	v_pk_mul_f32 v[40:41], v[40:41], v[160:161] op_sel_hi:[1,0]
	v_pk_mul_f32 v[38:39], v[38:39], v[160:161] op_sel_hi:[1,0]
	v_max_f32_e32 v34, 0, v34
	v_mul_f32_e32 v48, v48, v48
	v_cvt_pk_bf16_f32 v43, v47, v48
	v_addc_co_u32_e32 v47, vcc, 0, v165, vcc
	v_pk_mul_f32 v[36:37], v[36:37], v[160:161] op_sel_hi:[1,0]
	v_max_f32_e32 v0, 0, v38
	v_max_f32_e32 v38, 0, v39
	v_max_f32_e32 v39, 0, v40
	v_max_f32_e32 v40, 0, v41
	v_mul_f32_e32 v41, v34, v34
	v_max_f32_e32 v34, 0, v35
	v_cvt_pk_bf16_f32 v44, v49, v52
	v_cvt_pk_bf16_f32 v45, v53, v45
	ds_bpermute_b32 v42, v171, v42
	ds_bpermute_b32 v43, v171, v43
	ds_bpermute_b32 v44, v171, v44
	ds_bpermute_b32 v45, v171, v45
	v_pk_mul_f32 v[26:27], v[26:27], v[158:159] op_sel_hi:[1,0]
	s_mov_b64 s[10:11], 0x240000
	v_mul_f32_e32 v238, v34, v34
	v_max_f32_e32 v34, 0, v36
	v_mul_f32_e32 v0, v0, v0
	v_mul_f32_e32 v239, v34, v34
	v_max_f32_e32 v34, 0, v37
	v_pk_mul_f32 v[32:33], v[32:33], v[158:159] op_sel_hi:[1,0]
	v_pk_mul_f32 v[30:31], v[30:31], v[158:159] op_sel_hi:[1,0]
	v_max_f32_e32 v26, 0, v26
	v_lshl_add_u64 v[50:51], v[164:165], 0, s[10:11]
	v_mul_f32_e32 v38, v38, v38
	v_mul_f32_e32 v39, v39, v39
	v_mul_f32_e32 v40, v40, v40
	v_mul_f32_e32 v37, v34, v34
	v_cvt_pk_bf16_f32 v34, v0, v38
	v_cvt_pk_bf16_f32 v35, v39, v40
	v_cvt_pk_bf16_f32 v36, v41, v238
	v_pk_mul_f32 v[28:29], v[28:29], v[158:159] op_sel_hi:[1,0]
	v_max_f32_e32 v0, 0, v30
	v_max_f32_e32 v30, 0, v31
	v_max_f32_e32 v31, 0, v32
	v_max_f32_e32 v32, 0, v33
	v_mul_f32_e32 v33, v26, v26
	v_max_f32_e32 v26, 0, v27
	v_cvt_pk_bf16_f32 v37, v239, v37
	ds_bpermute_b32 v34, v171, v34
	ds_bpermute_b32 v35, v171, v35
	ds_bpermute_b32 v36, v171, v36
	ds_bpermute_b32 v37, v171, v37
	s_waitcnt lgkmcnt(4)
	global_store_dwordx4 v[46:47], v[42:45], off
	s_waitcnt lgkmcnt(0)
	global_store_dwordx4 v[46:47], v[34:37], off offset:256
	v_mul_f32_e32 v30, v30, v30
	s_mov_b32 s7, 0x280000
	v_mul_f32_e32 v36, v26, v26
	v_max_f32_e32 v26, 0, v28
	v_mul_f32_e32 v37, v26, v26
	v_max_f32_e32 v26, 0, v29
	v_pk_mul_f32 v[18:19], v[18:19], v[158:159] op_sel_hi:[1,0]
	v_mul_f32_e32 v0, v0, v0
	v_mul_f32_e32 v31, v31, v31
	v_mul_f32_e32 v29, v26, v26
	v_cvt_pk_bf16_f32 v26, v0, v30
	v_add_co_u32_e32 v30, vcc, s7, v164
	v_pk_mul_f32 v[24:25], v[24:25], v[158:159] op_sel_hi:[1,0]
	v_pk_mul_f32 v[22:23], v[22:23], v[158:159] op_sel_hi:[1,0]
	v_max_f32_e32 v18, 0, v18
	v_mul_f32_e32 v32, v32, v32
	v_cvt_pk_bf16_f32 v27, v31, v32
	v_addc_co_u32_e32 v31, vcc, 0, v165, vcc
	v_pk_mul_f32 v[20:21], v[20:21], v[158:159] op_sel_hi:[1,0]
	v_max_f32_e32 v0, 0, v22
	v_max_f32_e32 v22, 0, v23
	v_max_f32_e32 v23, 0, v24
	v_max_f32_e32 v24, 0, v25
	v_mul_f32_e32 v25, v18, v18
	v_max_f32_e32 v18, 0, v19
	v_cvt_pk_bf16_f32 v28, v33, v36
	v_cvt_pk_bf16_f32 v29, v37, v29
	ds_bpermute_b32 v26, v171, v26
	ds_bpermute_b32 v27, v171, v27
	ds_bpermute_b32 v28, v171, v28
	ds_bpermute_b32 v29, v171, v29
	v_pk_mul_f32 v[10:11], v[10:11], v[162:163] op_sel_hi:[1,0]
	s_mov_b64 s[10:11], 0x280000
	v_mul_f32_e32 v238, v18, v18
	v_max_f32_e32 v18, 0, v20
	v_mul_f32_e32 v0, v0, v0
	v_mul_f32_e32 v239, v18, v18
	v_max_f32_e32 v18, 0, v21
	v_pk_mul_f32 v[16:17], v[16:17], v[162:163] op_sel_hi:[1,0]
	v_pk_mul_f32 v[14:15], v[14:15], v[162:163] op_sel_hi:[1,0]
	v_max_f32_e32 v10, 0, v10
	v_lshl_add_u64 v[34:35], v[164:165], 0, s[10:11]
	v_mul_f32_e32 v22, v22, v22
	v_mul_f32_e32 v23, v23, v23
	v_mul_f32_e32 v24, v24, v24
	v_mul_f32_e32 v21, v18, v18
	v_cvt_pk_bf16_f32 v18, v0, v22
	v_cvt_pk_bf16_f32 v19, v23, v24
	v_cvt_pk_bf16_f32 v20, v25, v238
	v_pk_mul_f32 v[12:13], v[12:13], v[162:163] op_sel_hi:[1,0]
	v_max_f32_e32 v0, 0, v14
	v_max_f32_e32 v14, 0, v15
	v_max_f32_e32 v15, 0, v16
	v_max_f32_e32 v16, 0, v17
	v_mul_f32_e32 v17, v10, v10
	v_max_f32_e32 v10, 0, v11
	v_cvt_pk_bf16_f32 v21, v239, v21
	ds_bpermute_b32 v18, v171, v18
	ds_bpermute_b32 v19, v171, v19
	ds_bpermute_b32 v20, v171, v20
	ds_bpermute_b32 v21, v171, v21
	s_waitcnt lgkmcnt(4)
	global_store_dwordx4 v[30:31], v[26:29], off
	s_waitcnt lgkmcnt(0)
	global_store_dwordx4 v[30:31], v[18:21], off offset:256
	v_mul_f32_e32 v0, v0, v0
	v_mul_f32_e32 v14, v14, v14
	v_mul_f32_e32 v20, v10, v10
	v_max_f32_e32 v10, 0, v12
	v_mul_f32_e32 v21, v10, v10
	v_max_f32_e32 v10, 0, v13
	s_mov_b32 s7, 0x2c0000
	v_pk_mul_f32 v[4:5], v[4:5], v[162:163] op_sel_hi:[1,0]
	v_pk_mul_f32 v[2:3], v[2:3], v[162:163] op_sel_hi:[1,0]
	v_pk_mul_f32 v[6:7], v[6:7], v[162:163] op_sel_hi:[1,0]
	v_mul_f32_e32 v15, v15, v15
	v_mul_f32_e32 v13, v10, v10
	v_cvt_pk_bf16_f32 v10, v0, v14
	v_add_co_u32_e32 v14, vcc, s7, v164
	v_pk_mul_f32 v[8:9], v[8:9], v[162:163] op_sel_hi:[1,0]
	v_max_f32_e32 v0, 0, v2
	v_max_f32_e32 v2, 0, v3
	v_max_f32_e32 v3, 0, v4
	v_max_f32_e32 v4, 0, v5
	v_max_f32_e32 v5, 0, v6
	s_mov_b64 s[10:11], 0x2c0000
	v_mul_f32_e32 v16, v16, v16
	v_cvt_pk_bf16_f32 v11, v15, v16
	v_addc_co_u32_e32 v15, vcc, 0, v165, vcc
	v_mul_f32_e32 v2, v2, v2
	v_mul_f32_e32 v3, v3, v3
	v_mul_f32_e32 v4, v4, v4
	v_mul_f32_e32 v5, v5, v5
	v_max_f32_e32 v6, 0, v7
	v_max_f32_e32 v7, 0, v8
	v_max_f32_e32 v8, 0, v9
	v_lshl_add_u64 v[18:19], v[164:165], 0, s[10:11]
	v_cvt_pk_bf16_f32 v12, v17, v20
	v_cvt_pk_bf16_f32 v13, v21, v13
	ds_bpermute_b32 v10, v171, v10
	ds_bpermute_b32 v11, v171, v11
	ds_bpermute_b32 v12, v171, v12
	ds_bpermute_b32 v13, v171, v13
	v_mul_f32_e32 v0, v0, v0
	v_mul_f32_e32 v6, v6, v6
	v_mul_f32_e32 v7, v7, v7
	v_mul_f32_e32 v8, v8, v8
	v_cvt_pk_bf16_f32 v2, v0, v2
	v_cvt_pk_bf16_f32 v3, v3, v4
	v_cvt_pk_bf16_f32 v4, v5, v6
	v_cvt_pk_bf16_f32 v5, v7, v8
	s_mov_b64 s[10:11], -1
	s_andn2_b64 vcc, exec, s[4:5]
	ds_bpermute_b32 v2, v171, v2
	ds_bpermute_b32 v3, v171, v3
	ds_bpermute_b32 v4, v171, v4
	ds_bpermute_b32 v5, v171, v5
	s_waitcnt lgkmcnt(4)
	global_store_dwordx4 v[14:15], v[10:13], off
	s_waitcnt lgkmcnt(0)
	global_store_dwordx4 v[14:15], v[2:5], off offset:256
	s_cbranch_vccnz .LBB0_1160
	s_andn2_b64 vcc, exec, s[0:1]
	s_cbranch_vccnz .LBB0_1159
	s_barrier
	s_branch .LBB0_1159
